# P7 combined: K=32 fused MFMAs + scalar in-place Horner + loop-end waits 5/4/3/2
# speedup vs baseline: 1.0028x; 1.0028x over previous
; template <int DIR>
; __device__ __forceinline__ void s5_local_dir(const bf16_t* UZ, unsigned char* ws, int gw, int NGW, int lane) {
;     ...
;     for (int c = c0; c < c1; ++c) {
;         bf16x4 Uf[4];
; #pragma unroll
;         for (int m = 0; m < 4; ++m) Uf[m] = Un[m];
;         if (c + 1 < c1) load_uf(Un, UZ, chunk_rowbase(b, DIR, c + 1), g, lane);
;         float* e = ebase + (size_t)c * 128;
; #pragma unroll
;         for (int t = 0; t < 4; ++t) {
;             f32x4 cr = {0.f, 0.f, 0.f, 0.f}, ci = {0.f, 0.f, 0.f, 0.f};
; #pragma unroll
;             for (int m = 0; m < 4; ++m) {
;                 cr = __builtin_amdgcn_mfma_f32_16x16x16bf16_1k(Uf[m], Bre[m][t], cr, 0, 0, 0);
;                 ci = __builtin_amdgcn_mfma_f32_16x16x16bf16_1k(Uf[m], Bim[m][t], ci, 0, 0, 0);
;             }
;             f32x2 s2 = {DIR ? cr[3] : cr[0], DIR ? ci[3] : ci[0]};
; #pragma unroll
;             for (int ii = 1; ii < 4; ++ii) { const int i = DIR ? 3 - ii : ii;
;                 s2 = cmac(s2, (f32x2){a1r[t], a1r[t]}, (f32x2){-a1i[t], a1i[t]}, (f32x2){cr[i], ci[i]}); }
;             s2 = cmac(s2, (f32x2){wr_[t], wr_[t]}, (f32x2){-wi_[t], wi_[t]}, (f32x2){0.f, 0.f});
;             float sr = s2.x, si = s2.y;
;             sr += __shfl_xor(sr, 16); si += __shfl_xor(si, 16); sr += __shfl_xor(sr, 32); si += __shfl_xor(si, 32);
;             if (fq == 0) { e[16 * t + fr] = Rr[t]; e[64 + 16 * t + fr] = Ri[t]; }
;             const float nr = fmaf(a64r[t], Rr[t], fmaf(-a64i[t], Ri[t], sr)), ni = fmaf(a64r[t], Ri[t], fmaf(a64i[t], Rr[t], si)); Rr[t] = nr; Ri[t] = ni;
;         }
.LBB0_652:
	global_store_dword v[116:117], v240, off offset:-256
	global_store_dword v[116:117], v241, off
	s_waitcnt vmcnt(9)
	v_mfma_f32_16x16x32_bf16 v[140:143], v[108:111], v[26:29], 0
	v_mfma_f32_16x16x32_bf16 v[144:147], v[108:111], v[34:37], 0
	v_mfma_f32_16x16x32_bf16 v[196:199], v[108:111], v[48:51], 0
	v_mfma_f32_16x16x32_bf16 v[200:203], v[108:111], v[56:59], 0
	v_mfma_f32_16x16x32_bf16 v[208:211], v[108:111], v[70:73], 0
	v_mfma_f32_16x16x32_bf16 v[212:215], v[108:111], v[78:81], 0
	v_mfma_f32_16x16x32_bf16 v[228:231], v[108:111], v[92:95], 0
	v_mfma_f32_16x16x32_bf16 v[184:187], v[108:111], v[100:103], 0
	v_mfma_f32_16x16x32_bf16 v[140:143], v[112:115], v[30:33], v[140:143]
	v_mfma_f32_16x16x32_bf16 v[144:147], v[112:115], v[38:41], v[144:147]
	v_mfma_f32_16x16x32_bf16 v[196:199], v[112:115], v[52:55], v[196:199]
	v_mfma_f32_16x16x32_bf16 v[200:203], v[112:115], v[60:63], v[200:203]
	v_mfma_f32_16x16x32_bf16 v[208:211], v[112:115], v[74:77], v[208:211]
	v_mfma_f32_16x16x32_bf16 v[212:215], v[112:115], v[82:85], v[212:215]
	v_mfma_f32_16x16x32_bf16 v[228:231], v[112:115], v[96:99], v[228:231]
	v_mfma_f32_16x16x32_bf16 v[184:187], v[112:115], v[104:107], v[184:187]
	s_nop 6
	v_fma_f32 v142, v20, v143, v142
	v_fma_f32 v198, v42, v199, v198
	v_fma_f32 v210, v64, v211, v210
	v_fma_f32 v230, v86, v231, v230
	v_fma_f32 v146, v21, v147, v146
	v_fma_f32 v202, v43, v203, v202
	v_fma_f32 v214, v65, v215, v214
	v_fma_f32 v186, v87, v187, v186
	v_fma_f32 v142, v0, v147, v142
	v_fma_f32 v198, v4, v203, v198
	v_fma_f32 v210, v8, v215, v210
	v_fma_f32 v230, v12, v187, v230
	v_fma_f32 v146, v1, v143, v146
	v_fma_f32 v202, v5, v199, v202
	v_fma_f32 v214, v9, v211, v214
	v_fma_f32 v186, v13, v231, v186
	v_fma_f32 v141, v20, v142, v141
	v_fma_f32 v197, v42, v198, v197
	v_fma_f32 v209, v64, v210, v209
	v_fma_f32 v229, v86, v230, v229
	v_fma_f32 v145, v21, v146, v145
	v_fma_f32 v201, v43, v202, v201
	v_fma_f32 v213, v65, v214, v213
	v_fma_f32 v185, v87, v186, v185
	v_fma_f32 v141, v0, v146, v141
	v_fma_f32 v197, v4, v202, v197
	v_fma_f32 v209, v8, v214, v209
	v_fma_f32 v229, v12, v186, v229
	v_fma_f32 v145, v1, v142, v145
	v_fma_f32 v201, v5, v198, v201
	v_fma_f32 v213, v9, v210, v213
	v_fma_f32 v185, v13, v230, v185
	v_fma_f32 v140, v20, v141, v140
	v_fma_f32 v196, v42, v197, v196
	v_fma_f32 v208, v64, v209, v208
	v_fma_f32 v228, v86, v229, v228
	v_fma_f32 v144, v21, v145, v144
	v_fma_f32 v200, v43, v201, v200
	v_fma_f32 v212, v65, v213, v212
	v_fma_f32 v184, v87, v185, v184
	v_fma_f32 v140, v0, v145, v140
	v_fma_f32 v196, v4, v201, v196
	v_fma_f32 v208, v8, v213, v208
	v_fma_f32 v228, v12, v185, v228
	v_fma_f32 v144, v1, v141, v144
	v_fma_f32 v200, v5, v197, v200
	v_fma_f32 v212, v9, v209, v212
	v_fma_f32 v184, v13, v229, v184
	v_mul_f32_e32 v142, v22, v140
	v_mul_f32_e32 v198, v44, v196
	v_mul_f32_e32 v210, v66, v208
	v_mul_f32_e32 v229, v88, v228
	v_mul_f32_e32 v141, v23, v144
	v_mul_f32_e32 v197, v45, v200
	v_mul_f32_e32 v209, v67, v212
	v_mul_f32_e32 v230, v89, v184
	v_fma_f32 v141, v25, v140, v141
	v_fma_f32 v197, v47, v196, v197
	v_fma_f32 v209, v69, v208, v209
	v_fma_f32 v185, v91, v228, v230
	v_fma_f32 v140, v24, v144, v142
	v_fma_f32 v196, v46, v200, v198
	v_fma_f32 v208, v68, v212, v210
	v_fma_f32 v184, v90, v184, v229
	s_nop 1
	v_permlane32_swap_b32_e32 v140, v208
	v_permlane32_swap_b32_e32 v141, v209
	v_permlane32_swap_b32_e32 v196, v184
	v_permlane32_swap_b32_e32 v197, v185
	v_add_f32_e32 v140, v140, v208
	v_add_f32_e32 v196, v196, v184
	v_add_f32_e32 v141, v141, v209
	v_add_f32_e32 v197, v197, v185
	s_nop 0
	v_permlane16_swap_b32_e32 v140, v196
	v_permlane16_swap_b32_e32 v141, v197
	v_add_f32_e32 v140, v140, v196
	v_add_f32_e32 v141, v141, v197
	v_fma_f32 v244, -v243, v241, v140
	v_fma_f32 v245, v243, v240, v141
	v_fma_f32 v240, v242, v240, v244
	v_fma_f32 v241, v242, v241, v245
	v_lshl_add_u64 v[116:117], v[116:117], 0, s[2:3]
	v_subrev_u32_e32 v16, 64, v16
	s_and_b64 vcc, exec, s[36:37]
	s_cbranch_vccnz .LBB0_684
	s_mov_b32 s38, s49
	s_waitcnt vmcnt(5)
	v_mov_b32_e32 v110, v118
	v_mov_b32_e32 v111, v119
	s_waitcnt vmcnt(4)
	v_mov_b32_e32 v112, v120
	v_mov_b32_e32 v113, v121
	s_waitcnt vmcnt(3)
	v_mov_b32_e32 v114, v122
	v_mov_b32_e32 v115, v123
	s_waitcnt vmcnt(2)
	v_mov_b32_e32 v108, v124
	v_mov_b32_e32 v109, v125
	s_branch .LBB0_649

; template <int DIR>
; __device__ __forceinline__ void s5_local_dir(const bf16_t* UZ, unsigned char* ws, int gw, int NGW, int lane) {
;     ...
;     for (int c = c0; c < c1; ++c) {
;         bf16x4 Uf[4];
; #pragma unroll
;         for (int m = 0; m < 4; ++m) Uf[m] = Un[m];
;         if (c + 1 < c1) load_uf(Un, UZ, chunk_rowbase(b, DIR, c + 1), g, lane);
;         float* e = ebase + (size_t)c * 128;
; #pragma unroll
;         for (int t = 0; t < 4; ++t) {
;             f32x4 cr = {0.f, 0.f, 0.f, 0.f}, ci = {0.f, 0.f, 0.f, 0.f};
; #pragma unroll
;             for (int m = 0; m < 4; ++m) {
;                 cr = __builtin_amdgcn_mfma_f32_16x16x16bf16_1k(Uf[m], Bre[m][t], cr, 0, 0, 0);
;                 ci = __builtin_amdgcn_mfma_f32_16x16x16bf16_1k(Uf[m], Bim[m][t], ci, 0, 0, 0);
;             }
;             f32x2 s2 = {DIR ? cr[3] : cr[0], DIR ? ci[3] : ci[0]};
; #pragma unroll
;             for (int ii = 1; ii < 4; ++ii) { const int i = DIR ? 3 - ii : ii;
;                 s2 = cmac(s2, (f32x2){a1r[t], a1r[t]}, (f32x2){-a1i[t], a1i[t]}, (f32x2){cr[i], ci[i]}); }
;             s2 = cmac(s2, (f32x2){wr_[t], wr_[t]}, (f32x2){-wi_[t], wi_[t]}, (f32x2){0.f, 0.f});
;             float sr = s2.x, si = s2.y;
;             sr += __shfl_xor(sr, 16); si += __shfl_xor(si, 16); sr += __shfl_xor(sr, 32); si += __shfl_xor(si, 32);
;             if (fq == 0) { e[16 * t + fr] = Rr[t]; e[64 + 16 * t + fr] = Ri[t]; }
;             const float nr = fmaf(a64r[t], Rr[t], fmaf(-a64i[t], Ri[t], sr)), ni = fmaf(a64r[t], Ri[t], fmaf(a64i[t], Rr[t], si)); Rr[t] = nr; Ri[t] = ni;
;         }
.LBB0_674:
	global_store_dword v[116:117], v240, off offset:-256
	global_store_dword v[116:117], v241, off
	s_waitcnt vmcnt(9)
	v_mfma_f32_16x16x32_bf16 v[136:139], v[108:111], v[26:29], 0
	v_mfma_f32_16x16x32_bf16 v[140:143], v[108:111], v[34:37], 0
	v_mfma_f32_16x16x32_bf16 v[196:199], v[108:111], v[48:51], 0
	v_mfma_f32_16x16x32_bf16 v[200:203], v[108:111], v[56:59], 0
	v_mfma_f32_16x16x32_bf16 v[208:211], v[108:111], v[70:73], 0
	v_mfma_f32_16x16x32_bf16 v[212:215], v[108:111], v[78:81], 0
	v_mfma_f32_16x16x32_bf16 v[224:227], v[108:111], v[88:91], 0
	v_mfma_f32_16x16x32_bf16 v[184:187], v[108:111], v[100:103], 0
	v_mfma_f32_16x16x32_bf16 v[136:139], v[112:115], v[30:33], v[136:139]
	v_mfma_f32_16x16x32_bf16 v[140:143], v[112:115], v[38:41], v[140:143]
	v_mfma_f32_16x16x32_bf16 v[196:199], v[112:115], v[52:55], v[196:199]
	v_mfma_f32_16x16x32_bf16 v[200:203], v[112:115], v[60:63], v[200:203]
	v_mfma_f32_16x16x32_bf16 v[208:211], v[112:115], v[74:77], v[208:211]
	v_mfma_f32_16x16x32_bf16 v[212:215], v[112:115], v[82:85], v[212:215]
	v_mfma_f32_16x16x32_bf16 v[224:227], v[112:115], v[96:99], v[224:227]
	v_mfma_f32_16x16x32_bf16 v[184:187], v[112:115], v[104:107], v[184:187]
	s_nop 6
	v_fma_f32 v137, v18, v136, v137
	v_fma_f32 v197, v42, v196, v197
	v_fma_f32 v209, v64, v208, v209
	v_fma_f32 v225, v86, v224, v225
	v_fma_f32 v141, v19, v140, v141
	v_fma_f32 v201, v43, v200, v201
	v_fma_f32 v213, v65, v212, v213
	v_fma_f32 v185, v87, v184, v185
	v_fma_f32 v137, v0, v140, v137
	v_fma_f32 v197, v4, v200, v197
	v_fma_f32 v209, v8, v212, v209
	v_fma_f32 v225, v12, v184, v225
	v_fma_f32 v141, v1, v136, v141
	v_fma_f32 v201, v5, v196, v201
	v_fma_f32 v213, v9, v208, v213
	v_fma_f32 v185, v13, v224, v185
	v_fma_f32 v138, v18, v137, v138
	v_fma_f32 v198, v42, v197, v198
	v_fma_f32 v210, v64, v209, v210
	v_fma_f32 v226, v86, v225, v226
	v_fma_f32 v142, v19, v141, v142
	v_fma_f32 v202, v43, v201, v202
	v_fma_f32 v214, v65, v213, v214
	v_fma_f32 v186, v87, v185, v186
	v_fma_f32 v138, v0, v141, v138
	v_fma_f32 v198, v4, v201, v198
	v_fma_f32 v210, v8, v213, v210
	v_fma_f32 v226, v12, v185, v226
	v_fma_f32 v142, v1, v137, v142
	v_fma_f32 v202, v5, v197, v202
	v_fma_f32 v214, v9, v209, v214
	v_fma_f32 v186, v13, v225, v186
	v_fma_f32 v139, v18, v138, v139
	v_fma_f32 v199, v42, v198, v199
	v_fma_f32 v211, v64, v210, v211
	v_fma_f32 v227, v86, v226, v227
	v_fma_f32 v143, v19, v142, v143
	v_fma_f32 v203, v43, v202, v203
	v_fma_f32 v215, v65, v214, v215
	v_fma_f32 v187, v87, v186, v187
	v_fma_f32 v139, v0, v142, v139
	v_fma_f32 v199, v4, v202, v199
	v_fma_f32 v211, v8, v214, v211
	v_fma_f32 v227, v12, v186, v227
	v_fma_f32 v143, v1, v138, v143
	v_fma_f32 v203, v5, v198, v203
	v_fma_f32 v215, v9, v210, v215
	v_fma_f32 v187, v13, v226, v187
	v_mul_f32_e32 v136, v22, v139
	v_mul_f32_e32 v196, v44, v199
	v_mul_f32_e32 v208, v66, v211
	v_mul_f32_e32 v224, v92, v227
	v_mul_f32_e32 v137, v23, v143
	v_mul_f32_e32 v197, v45, v203
	v_mul_f32_e32 v209, v67, v215
	v_mul_f32_e32 v225, v93, v187
	v_fma_f32 v137, v25, v139, v137
	v_fma_f32 v197, v47, v199, v197
	v_fma_f32 v209, v69, v211, v209
	v_fma_f32 v185, v95, v227, v225
	v_fma_f32 v136, v24, v143, v136
	v_fma_f32 v196, v46, v203, v196
	v_fma_f32 v208, v68, v215, v208
	v_fma_f32 v184, v94, v187, v224
	s_nop 1
	v_permlane32_swap_b32_e32 v136, v208
	v_permlane32_swap_b32_e32 v137, v209
	v_permlane32_swap_b32_e32 v196, v184
	v_permlane32_swap_b32_e32 v197, v185
	v_add_f32_e32 v136, v136, v208
	v_add_f32_e32 v196, v196, v184
	v_add_f32_e32 v137, v137, v209
	v_add_f32_e32 v197, v197, v185
	s_nop 0
	v_permlane16_swap_b32_e32 v136, v196
	v_permlane16_swap_b32_e32 v137, v197
	v_add_f32_e32 v136, v136, v196
	v_add_f32_e32 v137, v137, v197
	v_fma_f32 v244, -v243, v241, v136
	v_fma_f32 v245, v243, v240, v137
	v_fma_f32 v240, v242, v240, v244
	v_fma_f32 v241, v242, v241, v245
	v_lshl_add_u64 v[116:117], v[116:117], 0, s[4:5]
	v_add_u32_e32 v20, 64, v20
	s_and_b64 vcc, exec, s[22:23]
	s_cbranch_vccnz .LBB0_702
	s_mov_b32 s24, s40
	s_waitcnt vmcnt(5)
	v_mov_b32_e32 v108, v118
	v_mov_b32_e32 v109, v119
	s_waitcnt vmcnt(4)
	v_mov_b32_e32 v112, v120
	v_mov_b32_e32 v113, v121
	s_waitcnt vmcnt(3)
	v_mov_b32_e32 v114, v122
	v_mov_b32_e32 v115, v123
	s_waitcnt vmcnt(2)
	v_mov_b32_e32 v110, v124
	v_mov_b32_e32 v111, v125
	s_branch .LBB0_671
